# LDS bank conflicts in attention: XOR-swizzle K-tile chunks (2-way conflict on ds_read_b128 removed) and split ds_read2_b64 V^T reads into ds_read_b64 pairs, for differential attention and retention
# speedup vs baseline: 1.0187x; 1.0090x over previous
; __global__ void __launch_bounds__(512, 2) mega_fwd(Params P) {
;     ...
;                             const int bh = u & 127, b = bh >> 2, h = bh & 3, qi_ = u >> 7, ii_ = qi_ >> 1, hb_ = qi_ & 1, qt = (ii_ & 1) ? (ii_ - 1 + hb_) : (15 - hb_ - ii_), q0 = qt * 128, nkt = qt + 1;
;                             const size_t rb = (size_t)b * SEQ;
;                             const float l2g = log2f(1.0f - exp2f(-5.0f - (float)h));
;                             f32x4 o[1][8]; float ll[1];
;                             attn_core3<64, 128, 2, 1, 128>(lds, Z + (rb + q0) * ZW + 512 + h * 64, ZW, Z + rb * ZW + 768 + h * 64, ZW, Z + rb * ZW + 1024 + h * 128, ZW, q0, nkt, 1.0f, l2g, o, ll);
.LBB0_788:
	s_ashr_i32 s6, s1, 8
	s_bfe_u32 s7, s1, 0x10007
	s_add_i32 s9, s6, s7
	s_xor_b32 s7, s7, 15
	s_and_b32 s12, s1, 3
	s_and_b32 s8, s1, 0x100
	s_add_i32 s9, s9, -1
	s_sub_i32 s6, s7, s6
	s_cmp_eq_u32 s8, 0
	s_cselect_b32 s22, s6, s9
	s_lshl_b32 s6, s1, 9
	v_cvt_f32_ubyte0_e32 v0, s12
	s_and_b32 s8, s6, 0xf800
	v_sub_f32_e32 v0, 0xc0a00000, v0
	s_mov_b32 s6, 0xc2fc0000
	v_cmp_gt_f32_e32 vcc, s6, v0
	v_mov_b32_e32 v2, 0x42800000
	s_lshl_b32 s31, s22, 7
	v_cndmask_b32_e32 v2, 0, v2, vcc
	v_add_f32_e32 v0, v0, v2
	v_exp_f32_e32 v0, v0
	s_and_b64 s[6:7], vcc, exec
	s_cselect_b32 s6, 0xffffffc0, 0
	v_mov_b32_e32 v11, v211
	v_ldexp_f32 v0, v0, s6
	v_sub_f32_e32 v10, 1.0, v0
	v_cmp_gt_f32_e32 vcc, s50, v10
	s_and_b64 s[6:7], vcc, exec
	s_cselect_b32 s43, 32, 0
	s_ashr_i32 s7, s31, 31
	s_add_u32 s6, s31, s8
	s_addc_u32 s7, s7, 0
	s_mul_i32 s9, s7, 0x1400
	s_mul_hi_u32 s10, s6, 0x1400
	s_add_i32 s10, s10, s9
	s_mul_i32 s9, s6, 0x1400
	s_add_u32 s9, s4, s9
	s_addc_u32 s11, s5, s10
	s_lshl_b32 s21, s12, 7
	s_add_u32 s10, s9, s21
	s_addc_u32 s11, s11, 0
	s_mulk_i32 s8, 0x1400
	s_add_u32 s13, s4, s8
	s_addc_u32 s15, s5, 0
	s_add_u32 s8, s13, s21
	s_addc_u32 s9, s15, 0
	s_lshl_b32 s12, s12, 8
	s_add_u32 s14, s13, s12
	s_addc_u32 s15, s15, 0
	v_readfirstlane_b32 s12, v11
	s_ashr_i32 s18, s12, 6
	v_and_b32_e32 v6, 15, v11
	s_lshl_b32 s33, s18, 4
	v_or_b32_e32 v0, s33, v6
	v_mov_b64_e32 v[2:3], s[10:11]
	v_mad_i64_i32 v[2:3], s[10:11], v0, s57, v[2:3]
	v_and_b32_e32 v0, 48, v11
	v_lshl_add_u64 v[2:3], v[2:3], 0, v[0:1]
	v_ashrrev_i32_e32 v0, 31, v11
	v_lshrrev_b32_e32 v0, 29, v0
	v_add_u32_e32 v0, v11, v0
	v_ashrrev_i32_e32 v8, 3, v0
	v_and_b32_e32 v0, -8, v0
	v_sub_u32_e32 v16, v11, v0
	global_load_dwordx4 v[34:37], v[2:3], off offset:1024
	global_load_dwordx4 v[38:41], v[2:3], off offset:1088
	v_mov_b64_e32 v[4:5], s[8:9]
	v_lshlrev_b32_e32 v2, 3, v16
	v_add_u32_e32 v0, 0x200, v11
	v_mad_i64_i32 v[12:13], s[10:11], v8, s57, v[4:5]
	v_ashrrev_i32_e32 v3, 31, v2
	v_ashrrev_i32_e32 v9, 31, v0
	v_lshl_add_u64 v[12:13], v[2:3], 1, v[12:13]
	v_lshrrev_b32_e32 v9, 29, v9
	global_load_dwordx4 v[42:45], v[12:13], off offset:1536
	v_add_u32_e32 v12, v0, v9
	v_ashrrev_i32_e32 v9, 3, v12
	v_and_b32_e32 v12, -8, v12
	v_sub_u32_e32 v17, v0, v12
	v_mad_i64_i32 v[12:13], s[10:11], v9, s57, v[4:5]
	s_ashr_i32 s10, s18, 31
	s_lshr_b32 s10, s10, 28
	v_lshlrev_b32_e32 v4, 3, v17
	s_add_i32 s10, s18, s10
	v_ashrrev_i32_e32 v5, 31, v4
	s_ashr_i32 s24, s10, 4
	s_add_i32 s12, s18, 8
	v_and_b32_e32 v7, 63, v11
	v_lshl_add_u64 v[12:13], v[4:5], 1, v[12:13]
	s_lshl_b32 s34, s24, 6
	s_ashr_i32 s13, s12, 31
	global_load_dwordx4 v[46:49], v[12:13], off offset:1536
	s_and_b32 s10, s10, -16
	v_or_b32_e32 v0, s34, v7
	v_mov_b64_e32 v[12:13], s[14:15]
	s_lshr_b32 s13, s13, 28
	s_sub_i32 s23, s18, s10
	v_mad_i64_i32 v[14:15], s[10:11], v0, s57, v[12:13]
	s_add_i32 s13, s12, s13
	s_lshl_b32 s10, s23, 3
	s_ashr_i32 s26, s13, 4
	s_add_i32 s16, s18, 16
	s_ashr_i32 s11, s10, 31
	s_lshl_b32 s40, s26, 6
	s_ashr_i32 s17, s16, 31
	s_add_i32 s18, s18, 24
	v_lshl_add_u64 v[14:15], s[10:11], 1, v[14:15]
	s_and_b32 s13, s13, -16
	v_or_b32_e32 v0, s40, v7
	s_lshr_b32 s17, s17, 28
	s_ashr_i32 s19, s18, 31
	global_load_dwordx4 v[50:53], v[14:15], off offset:2048
	s_sub_i32 s25, s12, s13
	v_mad_i64_i32 v[14:15], s[12:13], v0, s57, v[12:13]
	s_add_i32 s17, s16, s17
	s_lshr_b32 s19, s19, 28
	s_lshl_b32 s12, s25, 3
	s_ashr_i32 s28, s17, 4
	s_add_i32 s19, s18, s19
	s_ashr_i32 s13, s12, 31
	s_lshl_b32 s41, s28, 6
	s_ashr_i32 s30, s19, 4
	v_lshl_add_u64 v[14:15], s[12:13], 1, v[14:15]
	s_and_b32 s17, s17, -16
	v_or_b32_e32 v0, s41, v7
	s_lshl_b32 s42, s30, 6
	global_load_dwordx4 v[54:57], v[14:15], off offset:2048
	s_sub_i32 s27, s16, s17
	v_mad_i64_i32 v[14:15], s[16:17], v0, s57, v[12:13]
	s_and_b32 s19, s19, -16
	v_or_b32_e32 v0, s42, v7
	s_lshl_b32 s16, s27, 3
	s_sub_i32 s29, s18, s19
	v_mad_i64_i32 v[12:13], s[18:19], v0, s57, v[12:13]
	s_ashr_i32 s17, s16, 31
	s_lshl_b32 s18, s29, 3
	v_lshl_add_u64 v[14:15], s[16:17], 1, v[14:15]
	s_ashr_i32 s19, s18, 31
	global_load_dwordx4 v[58:61], v[14:15], off offset:2048
	v_lshl_add_u64 v[12:13], s[18:19], 1, v[12:13]
	global_load_dwordx4 v[62:65], v[12:13], off offset:2048
	s_movk_i32 s36, 0x90
	v_mul_lo_u32 v0, v8, s36
	v_lshlrev_b32_e32 v79, 4, v16
	v_lshrrev_b32_e32 v12, 2, v8
	v_lshrrev_b32_e32 v86, 3, v8
	v_xor_b32_e32 v86, v12, v86
	v_and_b32_e32 v86, 1, v86
	v_lshlrev_b32_e32 v86, 4, v86
	v_xor_b32_e32 v79, v79, v86
	s_mulk_i32 s23, 0x880
	v_add3_u32 v12, 0, v0, v79
	v_mul_lo_u32 v84, v9, s36
	v_lshlrev_b32_e32 v85, 4, v17
	v_xor_b32_e32 v85, v85, v86
	s_add_i32 s44, s23, 0
	s_lshl_b32 s24, s24, 7
	s_waitcnt lgkmcnt(0)
	s_barrier
; template <int D, int DV, int MODE, int NMAP, int KT> ...
;     ...
;     AT_LOAD(0);
;     __syncthreads();
;     AT_STORE(0);
;     if (nkt > 1) AT_LOAD(1);
	s_waitcnt vmcnt(0)
	ds_write_b128 v12, v[42:45]
	v_add3_u32 v12, 0, v84, v85
	s_add_i32 s44, s44, s24
	v_lshlrev_b32_e32 v86, 1, v7
	s_mulk_i32 s25, 0x880
	s_lshl_b32 s26, s26, 7
	s_mulk_i32 s27, 0x880
	s_lshl_b32 s28, s28, 7
	s_mulk_i32 s29, 0x880
	s_lshl_b32 s30, s30, 7
	ds_write_b128 v12, v[46:49]
	v_add_u32_e32 v12, s44, v86
	s_add_i32 s44, s25, 0
	s_add_i32 s44, s44, s26
	ds_write_b16 v12, v50 offset:18432
	ds_write_b16_d16_hi v12, v50 offset:18704
	ds_write_b16 v12, v51 offset:18976
	ds_write_b16_d16_hi v12, v51 offset:19248
	ds_write_b16 v12, v52 offset:19520
	ds_write_b16_d16_hi v12, v52 offset:19792
	ds_write_b16 v12, v53 offset:20064
	ds_write_b16_d16_hi v12, v53 offset:20336
	v_add_u32_e32 v12, s44, v86
	s_add_i32 s44, s27, 0
	s_add_i32 s44, s44, s28
	ds_write_b16 v12, v54 offset:18432
	ds_write_b16_d16_hi v12, v54 offset:18704
	ds_write_b16 v12, v55 offset:18976
	ds_write_b16_d16_hi v12, v55 offset:19248
	ds_write_b16 v12, v56 offset:19520
	ds_write_b16_d16_hi v12, v56 offset:19792
	ds_write_b16 v12, v57 offset:20064
	ds_write_b16_d16_hi v12, v57 offset:20336
	v_add_u32_e32 v12, s44, v86
	s_add_i32 s44, s29, 0
	s_add_i32 s44, s44, s30
	ds_write_b16 v12, v58 offset:18432
	ds_write_b16_d16_hi v12, v58 offset:18704
	ds_write_b16 v12, v59 offset:18976
	ds_write_b16_d16_hi v12, v59 offset:19248
	ds_write_b16 v12, v60 offset:19520
	ds_write_b16_d16_hi v12, v60 offset:19792
	ds_write_b16 v12, v61 offset:20064
	ds_write_b16_d16_hi v12, v61 offset:20336
	v_add_u32_e32 v12, s44, v86
	s_cmp_lt_i32 s22, 1
	ds_write_b16 v12, v62 offset:18432
	ds_write_b16_d16_hi v12, v62 offset:18704
	ds_write_b16 v12, v63 offset:18976
	ds_write_b16_d16_hi v12, v63 offset:19248
	ds_write_b16 v12, v64 offset:19520
	ds_write_b16_d16_hi v12, v64 offset:19792
	ds_write_b16 v12, v65 offset:20064
	ds_write_b16_d16_hi v12, v65 offset:20336
	s_cbranch_scc1 .LBB0_790
	v_add_u32_e32 v14, 0x80, v8
	v_mov_b64_e32 v[12:13], s[8:9]
	v_add_u32_e32 v16, 0x80, v9
	v_mad_i64_i32 v[14:15], s[44:45], v14, s57, v[12:13]
	v_mad_i64_i32 v[12:13], s[44:45], v16, s57, v[12:13]
	v_lshl_add_u64 v[14:15], v[2:3], 1, v[14:15]
	v_lshl_add_u64 v[12:13], v[4:5], 1, v[12:13]
	v_or_b32_e32 v18, 0x80, v7
	global_load_dwordx4 v[42:45], v[14:15], off offset:1536
	global_load_dwordx4 v[46:49], v[12:13], off offset:1536
	v_add_u32_e32 v14, s34, v18
	v_mov_b64_e32 v[12:13], s[14:15]
	v_mad_i64_i32 v[14:15], s[44:45], v14, s57, v[12:13]
	v_add_u32_e32 v16, s40, v18
	v_lshl_add_u64 v[14:15], s[10:11], 1, v[14:15]
	v_mad_i64_i32 v[16:17], s[44:45], v16, s57, v[12:13]
	v_lshl_add_u64 v[16:17], s[12:13], 1, v[16:17]
	global_load_dwordx4 v[50:53], v[14:15], off offset:2048
	global_load_dwordx4 v[54:57], v[16:17], off offset:2048
	v_add_u32_e32 v14, s41, v18
	v_mad_i64_i32 v[14:15], s[44:45], v14, s57, v[12:13]
	v_add_u32_e32 v16, s42, v18
	v_lshl_add_u64 v[14:15], s[16:17], 1, v[14:15]
	v_mad_i64_i32 v[12:13], s[44:45], v16, s57, v[12:13]
	v_lshl_add_u64 v[12:13], s[18:19], 1, v[12:13]
	global_load_dwordx4 v[58:61], v[14:15], off offset:2048
	global_load_dwordx4 v[62:65], v[12:13], off offset:2048
; template <int D, int DV, int MODE, int NMAP, int KT> ...
;     ...
;     if (MODE == 2) {
; #pragma unroll
;         for (int nb = 0; nb < NB; ++nb)
; #pragma unroll
;             for (int j = 0; j < 4; ++j) ck[nb][j] = __builtin_amdgcn_exp2f(-l2g * (float)(nb * 16 + g4 * 4 + j));
;     }
.LBB0_790:
	s_cmp_lt_i32 s22, 0
	s_cbranch_scc1 .LBB0_786
	v_ldexp_f32 v10, v10, s43
	v_log_f32_e32 v10, v10
	v_mov_b32_e32 v12, 0x42000000
	v_bfe_u32 v11, v11, 4, 2
	v_cndmask_b32_e32 v12, 0, v12, vcc
	v_lshlrev_b32_e32 v89, 2, v11
	v_sub_f32_e32 v88, v10, v12
	v_cvt_f32_ubyte0_e32 v10, v89
	v_mul_f32_e64 v10, -v88, v10
	v_exp_f32_e32 v90, v10
	v_or_b32_e32 v10, 1, v89
	v_cvt_f32_ubyte0_e32 v10, v10
	v_mul_f32_e64 v10, -v88, v10
	v_exp_f32_e32 v91, v10
	v_or_b32_e32 v10, 2, v89
	v_cvt_f32_ubyte0_e32 v10, v10
	v_mul_f32_e64 v10, -v88, v10
	v_exp_f32_e32 v92, v10
	v_or_b32_e32 v10, 3, v89
	v_cvt_f32_ubyte0_e32 v10, v10
	v_mul_f32_e64 v10, -v88, v10
	v_exp_f32_e32 v93, v10
	v_or_b32_e32 v10, 16, v89
	v_cvt_f32_ubyte0_e32 v10, v10
	v_mul_f32_e64 v10, -v88, v10
	v_exp_f32_e32 v94, v10
	v_or_b32_e32 v10, 17, v89
	v_cvt_f32_ubyte0_e32 v10, v10
	v_mul_f32_e64 v10, -v88, v10
	v_exp_f32_e32 v95, v10
	v_or_b32_e32 v10, 18, v89
	v_cvt_f32_ubyte0_e32 v10, v10
	v_mul_f32_e64 v10, -v88, v10
	v_exp_f32_e32 v96, v10
	v_or_b32_e32 v10, 19, v89
	v_cvt_f32_ubyte0_e32 v10, v10
	v_mul_f32_e64 v10, -v88, v10
	v_exp_f32_e32 v97, v10
	v_or_b32_e32 v10, 32, v89
	v_cvt_f32_ubyte0_e32 v10, v10
	v_mul_f32_e64 v10, -v88, v10
	v_exp_f32_e32 v98, v10
	v_or_b32_e32 v10, 33, v89
	v_cvt_f32_ubyte0_e32 v10, v10
	v_mul_f32_e64 v10, -v88, v10
	v_exp_f32_e32 v99, v10
	v_or_b32_e32 v10, 34, v89
	v_cvt_f32_ubyte0_e32 v10, v10
	v_mul_f32_e64 v10, -v88, v10
	v_exp_f32_e32 v100, v10
	v_or_b32_e32 v10, 35, v89
	v_cvt_f32_ubyte0_e32 v10, v10
	v_mul_f32_e64 v10, -v88, v10
	v_exp_f32_e32 v101, v10
	v_or_b32_e32 v10, 48, v89
	v_cvt_f32_ubyte0_e32 v10, v10
	v_mul_f32_e64 v10, -v88, v10
	v_exp_f32_e32 v102, v10
	v_or_b32_e32 v10, 49, v89
	v_cvt_f32_ubyte0_e32 v10, v10
	v_mul_f32_e64 v10, -v88, v10
	v_exp_f32_e32 v103, v10
	v_or_b32_e32 v10, 50, v89
	v_cvt_f32_ubyte0_e32 v10, v10
	v_mul_f32_e64 v10, -v88, v10
	v_exp_f32_e32 v104, v10
	v_or_b32_e32 v10, 51, v89
	v_cvt_f32_ubyte0_e32 v10, v10
	v_mul_f32_e64 v10, -v88, v10
	v_exp_f32_e32 v105, v10
	v_or_b32_e32 v10, 64, v89
	v_cvt_f32_ubyte0_e32 v10, v10
	v_mul_f32_e64 v10, -v88, v10
	v_exp_f32_e32 v106, v10
	v_or_b32_e32 v10, 0x41, v89
	v_cvt_f32_ubyte0_e32 v10, v10
	v_mul_f32_e64 v10, -v88, v10
	v_exp_f32_e32 v107, v10
	v_or_b32_e32 v10, 0x42, v89
	v_cvt_f32_ubyte0_e32 v10, v10
	v_mul_f32_e64 v10, -v88, v10
	v_exp_f32_e32 v108, v10
	v_or_b32_e32 v10, 0x43, v89
	v_cvt_f32_ubyte0_e32 v10, v10
	v_mul_f32_e64 v10, -v88, v10
	v_exp_f32_e32 v109, v10
	v_or_b32_e32 v10, 0x50, v89
	v_cvt_f32_ubyte0_e32 v10, v10
	v_mul_f32_e64 v10, -v88, v10
	v_exp_f32_e32 v110, v10
	v_or_b32_e32 v10, 0x51, v89
	v_cvt_f32_ubyte0_e32 v10, v10
	v_mul_f32_e64 v10, -v88, v10
	v_exp_f32_e32 v111, v10
	v_or_b32_e32 v10, 0x52, v89
	v_cvt_f32_ubyte0_e32 v10, v10
	v_mul_f32_e64 v10, -v88, v10
	v_exp_f32_e32 v112, v10
	v_or_b32_e32 v10, 0x53, v89
	v_cvt_f32_ubyte0_e32 v10, v10
	v_mul_f32_e64 v10, -v88, v10
	v_exp_f32_e32 v113, v10
	v_or_b32_e32 v10, 0x60, v89
	v_cvt_f32_ubyte0_e32 v10, v10
	v_mul_f32_e64 v10, -v88, v10
	v_exp_f32_e32 v114, v10
	v_or_b32_e32 v10, 0x61, v89
	v_cvt_f32_ubyte0_e32 v10, v10
	v_mul_f32_e64 v10, -v88, v10
	v_exp_f32_e32 v115, v10
	v_or_b32_e32 v10, 0x62, v89
	v_cvt_f32_ubyte0_e32 v10, v10
	v_mul_f32_e64 v10, -v88, v10
	v_exp_f32_e32 v116, v10
	v_or_b32_e32 v10, 0x63, v89
	v_cvt_f32_ubyte0_e32 v10, v10
	v_mul_f32_e64 v10, -v88, v10
	v_exp_f32_e32 v117, v10
	v_or_b32_e32 v10, 0x70, v89
	v_cvt_f32_ubyte0_e32 v10, v10
	v_mul_f32_e64 v10, -v88, v10
	v_exp_f32_e32 v118, v10
	v_or_b32_e32 v10, 0x71, v89
	v_cvt_f32_ubyte0_e32 v10, v10
	s_add_i32 s31, s33, s31
	v_mul_f32_e64 v10, -v88, v10
	s_or_b32 s33, s31, 15
	v_lshl_add_u64 v[80:81], v[2:3], 1, s[8:9]
	v_lshl_add_u64 v[82:83], v[4:5], 1, s[8:9]
	s_lshl_b64 s[8:9], s[10:11], 1
	v_exp_f32_e32 v119, v10
	v_or_b32_e32 v10, 0x72, v89
	s_add_u32 s8, s14, s8
	v_cvt_f32_ubyte0_e32 v10, v10
	s_addc_u32 s9, s15, s9
	s_lshl_b64 s[10:11], s[12:13], 1
	v_mul_f32_e64 v10, -v88, v10
	s_add_u32 s10, s14, s10
	v_exp_f32_e32 v120, v10
	v_or_b32_e32 v10, 0x73, v89
	s_addc_u32 s11, s15, s11
	s_lshl_b64 s[12:13], s[16:17], 1
	v_cvt_f32_ubyte0_e32 v10, v10
	s_add_u32 s12, s14, s12
	v_mul_f32_e64 v10, -v88, v10
	s_addc_u32 s13, s15, s13
	s_lshl_b64 s[16:17], s[18:19], 1
	v_exp_f32_e32 v121, v10
	s_add_u32 s14, s14, s16
	v_mov_b32_e32 v2, 0x900
	s_movk_i32 s16, 0x90
	v_mad_u32_u24 v124, v6, s16, v2
	v_mov_b32_e32 v2, 0x1200
	s_addc_u32 s15, s15, s17
	v_mad_u32_u24 v125, v6, s16, v2
	v_mov_b32_e32 v2, 0x1b00
	s_addk_i32 s42, 0x100
	s_addk_i32 s41, 0x100
	s_addk_i32 s40, 0x100
	s_addk_i32 s34, 0x100
	v_mov_b32_e32 v30, 0
	v_lshlrev_b32_e32 v87, 3, v11
	v_or_b32_e32 v122, s31, v6
	v_mul_u32_u24_e32 v123, 0x90, v6
	v_mad_u32_u24 v126, v6, s16, v2
	v_lshrrev_b32_e32 v127, 2, v6
	v_lshrrev_b32_e32 v128, 3, v6
	v_xor_b32_e32 v127, v127, v128
	v_and_b32_e32 v127, 1, v127
	v_xor_b32_e32 v128, v127, v11
	v_sub_u32_e32 v128, v128, v11
	v_lshlrev_b32_e32 v128, 4, v128
	v_add_u32_e32 v123, v123, v128
	v_add_u32_e32 v124, v124, v128
	v_add_u32_e32 v125, v125, v128
	v_add_u32_e32 v126, v126, v128
	v_mul_u32_u24_e32 v127, 0x110, v6
	v_add_u32_e32 v128, s42, v7
	v_add_u32_e32 v129, s41, v7
	v_add_u32_e32 v130, s40, v7
	v_add_u32_e32 v131, s34, v7
	v_add_u32_e32 v132, 0x100, v9
	v_add_u32_e32 v133, 0x100, v8
	s_add_i32 s18, s22, 1
	v_add_u32_e32 v134, s31, v6
	s_mov_b32 s19, 0
	s_mov_b32 s16, 0
	v_mov_b32_e32 v31, v30
	v_mov_b32_e32 v32, v30
	v_mov_b32_e32 v33, v30
	v_mov_b32_e32 v26, v30
	v_mov_b32_e32 v27, v30
	v_mov_b32_e32 v28, v30
	v_mov_b32_e32 v29, v30
	v_mov_b32_e32 v22, v30
	v_mov_b32_e32 v23, v30
	v_mov_b32_e32 v24, v30
	v_mov_b32_e32 v25, v30
	v_mov_b32_e32 v18, v30
	v_mov_b32_e32 v19, v30
	v_mov_b32_e32 v20, v30
	v_mov_b32_e32 v21, v30
	v_mov_b32_e32 v14, v30
	v_mov_b32_e32 v15, v30
	v_mov_b32_e32 v16, v30
	v_mov_b32_e32 v17, v30
	v_mov_b32_e32 v10, v30
	v_mov_b32_e32 v11, v30
	v_mov_b32_e32 v12, v30
	v_mov_b32_e32 v13, v30
	v_mov_b32_e32 v6, v30
	v_mov_b32_e32 v7, v30
	v_mov_b32_e32 v8, v30
	v_mov_b32_e32 v9, v30
	v_mov_b32_e32 v2, v30
	v_mov_b32_e32 v3, v30
	v_mov_b32_e32 v4, v30
	v_mov_b32_e32 v5, v30

; #define AT_SLOAD(bi_, sl_) do { _Pragma("unroll") for (int x_ = 0; x_ < NBB; ++x_) _Pragma("unroll") for (int kk = 0; kk < KD; ++kk) \
;                     kfr[sl_][x_][kk] = *(const LAS bf16x8*)(Ks + (((bi_) * NBB + x_) * 16 + r) * KSTR + mp * D + kk * 32 + g4 * 8); } while (0)
; template <int D, int DV, int MODE, int NMAP, int KT> ...
;     ...
;                 AT_SLOAD(0, 0);
; #pragma unroll
;                 for (int bi = 0; bi < NSB; ++bi) {
;                     if (bi + 1 < NSB) AT_SLOAD(bi + 1, (bi + 1) & 1);
;                     __builtin_amdgcn_sched_barrier(0);
;                     __builtin_amdgcn_s_setprio(1);
; #pragma unroll
;                     for (int x_ = 0; x_ < NBB; ++x_) { const int nb = bi * NBB + x_;
;                         s[nb] = __builtin_amdgcn_mfma_f32_16x16x32_bf16(kfr[bi & 1][x_][0], qf[mp][0], (f32x4){0.f, 0.f, 0.f, 0.f}, 0, 0, 0);
; #pragma unroll
;                         for (int kk = 1; kk < KD; ++kk) s[nb] = __builtin_amdgcn_mfma_f32_16x16x32_bf16(kfr[bi & 1][x_][kk], qf[mp][kk], s[nb], 0, 0, 0); }
;                     __builtin_amdgcn_s_setprio(0);
;                     __builtin_amdgcn_sched_barrier(0);
;     ...
;                     const float rowf = __builtin_amdgcn_exp2f(l2g * (float)(myrow - kt * KT));
; #pragma unroll
;                     for (int nb = 0; nb < NB; ++nb)
; #pragma unroll
;                         for (int j = 0; j < 4; ++j) { float p = s[nb][j] * (rowf * ck[nb][j]); if (diag && (kt * KT + nb * 16 + g4 * 4 + j > myrow)) p = 0.f; s[nb][j] = p; }
.LBB0_795:
	s_cmp_gt_i32 s19, s33
	s_cbranch_scc1 .LBB0_797
	s_bitcmp1_b32 s16, 0
	s_cselect_b32 s16, 0xd000, 0
	s_add_i32 s40, s16, 0
	v_lshlrev_b32_e32 v135, 1, v87
	v_add_u32_e32 v184, s40, v135
	v_add_u32_e32 v156, v184, v123
	ds_read_b128 v[66:69], v156
	ds_read_b128 v[70:73], v156 offset:64
	ds_read_b128 v[136:139], v156 offset:2304
	ds_read_b128 v[140:143], v156 offset:2368
	ds_read_b128 v[144:147], v156 offset:4608
	ds_read_b128 v[148:151], v156 offset:4672
	ds_read_b128 v[152:155], v156 offset:6912
	ds_read_b128 v[156:159], v156 offset:6976
	v_add3_u32 v135, s40, v123, v135
	ds_read_b128 v[160:163], v135 offset:9216
	ds_read_b128 v[164:167], v135 offset:9280
	v_add_u32_e32 v135, v184, v124
	ds_read_b128 v[168:171], v135 offset:9216
	ds_read_b128 v[172:175], v135 offset:9280
	v_add_u32_e32 v135, v184, v125
	ds_read_b128 v[176:179], v135 offset:9216
	ds_read_b128 v[180:183], v135 offset:9280
	v_add_u32_e32 v135, v184, v126
	ds_read_b128 v[194:197], v135 offset:9216
	ds_read_b128 v[198:201], v135 offset:9280
	s_add_i32 s16, s19, 0x7f
	s_setprio 1
	s_waitcnt lgkmcnt(0)
	v_mfma_f32_16x16x32_bf16 v[66:69], v[66:69], v[34:37], 0
	v_mfma_f32_16x16x32_bf16 v[66:69], v[70:73], v[38:41], v[66:69]
	v_mfma_f32_16x16x32_bf16 v[70:73], v[136:139], v[34:37], 0
	v_mfma_f32_16x16x32_bf16 v[70:73], v[140:143], v[38:41], v[70:73]
	v_mfma_f32_16x16x32_bf16 v[136:139], v[144:147], v[34:37], 0
	v_mfma_f32_16x16x32_bf16 v[140:143], v[152:155], v[34:37], 0
	v_mfma_f32_16x16x32_bf16 v[136:139], v[148:151], v[38:41], v[136:139]
	v_mfma_f32_16x16x32_bf16 v[140:143], v[156:159], v[38:41], v[140:143]
	s_setprio 0
	s_setprio 1
	v_mfma_f32_16x16x32_bf16 v[144:147], v[160:163], v[34:37], 0
	v_mfma_f32_16x16x32_bf16 v[148:151], v[168:171], v[34:37], 0
	v_mfma_f32_16x16x32_bf16 v[152:155], v[176:179], v[34:37], 0
	v_mfma_f32_16x16x32_bf16 v[156:159], v[194:197], v[34:37], 0
	v_mfma_f32_16x16x32_bf16 v[144:147], v[164:167], v[38:41], v[144:147]
	v_mfma_f32_16x16x32_bf16 v[148:151], v[172:175], v[38:41], v[148:151]
	v_mfma_f32_16x16x32_bf16 v[152:155], v[180:183], v[38:41], v[152:155]
	v_mfma_f32_16x16x32_bf16 v[156:159], v[198:201], v[38:41], v[156:159]
	s_setprio 0
	v_cvt_f32_i32_e32 v135, v134
	s_cmp_gt_i32 s16, s31
	v_add_u32_e32 v160, s19, v89
	s_cselect_b64 s[16:17], -1, 0
	v_mul_f32_e32 v135, v88, v135
	v_exp_f32_e32 v135, v135
	v_cmp_gt_i32_e32 vcc, v160, v122
	s_and_b64 s[42:43], s[16:17], vcc
	v_cmp_ge_i32_e32 vcc, v160, v122
	v_mul_f32_e32 v161, v90, v135
	v_mul_f32_e32 v66, v161, v66
	v_mul_f32_e32 v161, v92, v135
	v_mul_f32_e32 v68, v161, v68
	v_add_u32_e32 v161, 2, v160
	v_mul_f32_e32 v162, v91, v135
	v_cndmask_b32_e64 v66, v66, 0, s[42:43]
	s_and_b64 s[42:43], s[16:17], vcc
	v_cmp_gt_i32_e32 vcc, v161, v122
	v_mul_f32_e32 v161, v93, v135
	v_mul_f32_e32 v67, v162, v67
	v_mul_f32_e32 v69, v161, v69
	v_add_u32_e32 v161, 3, v160
	v_cndmask_b32_e64 v67, v67, 0, s[42:43]
	s_and_b64 s[42:43], s[16:17], vcc
	v_cmp_gt_i32_e32 vcc, v161, v122
	v_add_u32_e32 v161, 16, v160
	v_cndmask_b32_e64 v68, v68, 0, s[42:43]
	s_and_b64 s[42:43], s[16:17], vcc
	v_cmp_gt_i32_e32 vcc, v161, v122
	v_mul_f32_e32 v161, v95, v135
	v_mul_f32_e32 v71, v161, v71
	v_add_u32_e32 v161, 17, v160
	v_cndmask_b32_e64 v69, v69, 0, s[42:43]
	v_mul_f32_e32 v162, v94, v135
	s_and_b64 s[42:43], s[16:17], vcc
	v_cmp_gt_i32_e32 vcc, v161, v122
	v_mul_f32_e32 v161, v96, v135
	v_mul_f32_e32 v70, v162, v70
	v_mul_f32_e32 v72, v161, v72
	v_add_u32_e32 v161, 18, v160
	v_cndmask_b32_e64 v70, v70, 0, s[42:43]
	s_and_b64 s[42:43], s[16:17], vcc
	v_cmp_gt_i32_e32 vcc, v161, v122
	v_mul_f32_e32 v161, v97, v135
	v_mul_f32_e32 v73, v161, v73
	v_add_u32_e32 v161, 19, v160
	v_cndmask_b32_e64 v71, v71, 0, s[42:43]
	s_and_b64 s[42:43], s[16:17], vcc
	v_cmp_gt_i32_e32 vcc, v161, v122
	v_add_u32_e32 v161, 32, v160
	v_cndmask_b32_e64 v72, v72, 0, s[42:43]
	s_and_b64 s[42:43], s[16:17], vcc
	v_mul_f32_e32 v162, v98, v135
	v_cmp_gt_i32_e32 vcc, v161, v122
	v_cndmask_b32_e64 v73, v73, 0, s[42:43]
	v_mul_f32_e32 v136, v162, v136
	s_and_b64 s[42:43], s[16:17], vcc
	v_cndmask_b32_e64 v161, v136, 0, s[42:43]
	v_mul_f32_e32 v136, v99, v135
	v_mul_f32_e32 v136, v136, v137
	v_add_u32_e32 v137, 33, v160
	v_cmp_gt_i32_e32 vcc, v137, v122
	s_and_b64 s[42:43], s[16:17], vcc
	v_add_u32_e32 v137, 34, v160
	v_cndmask_b32_e64 v162, v136, 0, s[42:43]
	v_mul_f32_e32 v136, v100, v135
	v_cmp_gt_i32_e32 vcc, v137, v122
	v_mul_f32_e32 v136, v136, v138
	s_and_b64 s[42:43], s[16:17], vcc
	v_add_u32_e32 v137, 35, v160
	v_cndmask_b32_e64 v163, v136, 0, s[42:43]
	v_mul_f32_e32 v136, v101, v135
	v_cmp_gt_i32_e32 vcc, v137, v122
	v_mul_f32_e32 v136, v136, v139
	s_and_b64 s[42:43], s[16:17], vcc
	v_cndmask_b32_e64 v164, v136, 0, s[42:43]
	v_add_u32_e32 v136, 48, v160
	v_mul_f32_e32 v137, v102, v135
	v_cmp_gt_i32_e32 vcc, v136, v122
	v_mul_f32_e32 v137, v137, v140
	s_and_b64 s[42:43], s[16:17], vcc
	v_cndmask_b32_e64 v165, v137, 0, s[42:43]
	v_add_u32_e32 v137, 49, v160
	v_mul_f32_e32 v136, v103, v135
	v_cmp_gt_i32_e32 vcc, v137, v122
	v_mul_f32_e32 v136, v136, v141
	s_and_b64 s[42:43], s[16:17], vcc
	v_add_u32_e32 v137, 50, v160
	v_cndmask_b32_e64 v166, v136, 0, s[42:43]
	v_mul_f32_e32 v136, v104, v135
	v_cmp_gt_i32_e32 vcc, v137, v122
	v_mul_f32_e32 v136, v136, v142
	s_and_b64 s[42:43], s[16:17], vcc
	v_add_u32_e32 v137, 51, v160
	v_cndmask_b32_e64 v167, v136, 0, s[42:43]
	v_mul_f32_e32 v136, v105, v135
	v_cmp_gt_i32_e32 vcc, v137, v122
	v_mul_f32_e32 v136, v136, v143
	s_and_b64 s[42:43], s[16:17], vcc
	v_cndmask_b32_e64 v143, v136, 0, s[42:43]
	v_add_u32_e32 v136, 64, v160
	v_mul_f32_e32 v137, v106, v135
	v_cmp_gt_i32_e32 vcc, v136, v122
; __device__ __forceinline__ unsigned cvt_pk_bf16(float lo, float hi) { unsigned r; asm volatile("v_cvt_pk_bf16_f32 %0, %1, %2" : "=v"(r) : "v"(lo), "v"(hi)); return r; }
; template <int D, int DV, int MODE, int NMAP, int KT> ...
;     ...
;                         for (int j = 0; j < 4; ++j) { float p = s[nb][j] * (rowf * ck[nb][j]); if (diag && (kt * KT + nb * 16 + g4 * 4 + j > myrow)) p = 0.f; s[nb][j] = p; }
;                 }
; #pragma unroll
;                 for (int kk = 0; kk < KK2; ++kk) { u32x4 wv; wv.x = cvt_pk_bf16(s[2 * kk][0], s[2 * kk][1]); wv.y = cvt_pk_bf16(s[2 * kk][2], s[2 * kk][3]);
;                     wv.z = cvt_pk_bf16(s[2 * kk + 1][0], s[2 * kk + 1][1]); wv.w = cvt_pk_bf16(s[2 * kk + 1][2], s[2 * kk + 1][3]); pb[mp][kk] = __builtin_bit_cast(bf16x8, wv); }
;             }
;             {
;                 constexpr int CBB = 4, NCB = (DV / 16) / CBB, NVB = KK2 * NCB;
;                 bf16x8 vfr[2][CBB];
;     ...
;                 AT_VLOAD(0, 0);
; #pragma unroll
;                 for (int b_ = 0; b_ < NVB; ++b_) {
;                     if (b_ + 1 < NVB) AT_VLOAD(b_ + 1, (b_ + 1) & 1);
	v_mul_f32_e32 v137, v137, v144
	s_and_b64 s[42:43], s[16:17], vcc
	v_cndmask_b32_e64 v144, v137, 0, s[42:43]
	v_add_u32_e32 v137, 0x41, v160
	v_mul_f32_e32 v136, v107, v135
	v_cmp_gt_i32_e32 vcc, v137, v122
	v_mul_f32_e32 v136, v136, v145
	s_and_b64 s[42:43], s[16:17], vcc
	v_add_u32_e32 v137, 0x42, v160
	v_cndmask_b32_e64 v145, v136, 0, s[42:43]
	v_mul_f32_e32 v136, v108, v135
	v_cmp_gt_i32_e32 vcc, v137, v122
	v_mul_f32_e32 v136, v136, v146
	s_and_b64 s[42:43], s[16:17], vcc
	v_add_u32_e32 v137, 0x43, v160
	v_cndmask_b32_e64 v146, v136, 0, s[42:43]
	v_mul_f32_e32 v136, v109, v135
	v_cmp_gt_i32_e32 vcc, v137, v122
	v_mul_f32_e32 v136, v136, v147
	s_and_b64 s[42:43], s[16:17], vcc
	v_cndmask_b32_e64 v147, v136, 0, s[42:43]
	v_add_u32_e32 v136, 0x50, v160
	v_mul_f32_e32 v137, v110, v135
	v_cmp_gt_i32_e32 vcc, v136, v122
	v_mul_f32_e32 v137, v137, v148
	s_and_b64 s[42:43], s[16:17], vcc
	v_cndmask_b32_e64 v148, v137, 0, s[42:43]
	v_add_u32_e32 v137, 0x51, v160
	v_mul_f32_e32 v136, v111, v135
	v_cmp_gt_i32_e32 vcc, v137, v122
	v_mul_f32_e32 v136, v136, v149
	s_and_b64 s[42:43], s[16:17], vcc
	v_add_u32_e32 v137, 0x52, v160
	v_cndmask_b32_e64 v149, v136, 0, s[42:43]
	v_mul_f32_e32 v136, v112, v135
	v_cmp_gt_i32_e32 vcc, v137, v122
	v_mul_f32_e32 v136, v136, v150
	s_and_b64 s[42:43], s[16:17], vcc
	v_add_u32_e32 v137, 0x53, v160
	v_cndmask_b32_e64 v150, v136, 0, s[42:43]
	v_mul_f32_e32 v136, v113, v135
	v_cmp_gt_i32_e32 vcc, v137, v122
	v_mul_f32_e32 v136, v136, v151
	s_and_b64 s[42:43], s[16:17], vcc
	v_cndmask_b32_e64 v151, v136, 0, s[42:43]
	v_add_u32_e32 v136, 0x60, v160
	v_mul_f32_e32 v137, v114, v135
	v_cmp_gt_i32_e32 vcc, v136, v122
	v_mul_f32_e32 v137, v137, v152
	s_and_b64 s[42:43], s[16:17], vcc
	v_cndmask_b32_e64 v152, v137, 0, s[42:43]
	v_add_u32_e32 v137, 0x61, v160
	v_mul_f32_e32 v136, v115, v135
	v_cmp_gt_i32_e32 vcc, v137, v122
	v_mul_f32_e32 v136, v136, v153
	s_and_b64 s[42:43], s[16:17], vcc
	v_add_u32_e32 v137, 0x62, v160
	v_cndmask_b32_e64 v153, v136, 0, s[42:43]
	v_mul_f32_e32 v136, v116, v135
	v_cmp_gt_i32_e32 vcc, v137, v122
	v_mul_f32_e32 v136, v136, v154
	s_and_b64 s[42:43], s[16:17], vcc
	v_add_u32_e32 v137, 0x63, v160
	v_cndmask_b32_e64 v154, v136, 0, s[42:43]
	v_mul_f32_e32 v136, v117, v135
	v_cmp_gt_i32_e32 vcc, v137, v122
	v_mul_f32_e32 v136, v136, v155
	s_and_b64 s[42:43], s[16:17], vcc
	v_cndmask_b32_e64 v155, v136, 0, s[42:43]
	v_add_u32_e32 v136, 0x70, v160
	v_mul_f32_e32 v137, v118, v135
	v_cmp_gt_i32_e32 vcc, v136, v122
	v_mul_f32_e32 v137, v137, v156
	s_and_b64 s[42:43], s[16:17], vcc
	v_cndmask_b32_e64 v156, v137, 0, s[42:43]
	v_add_u32_e32 v137, 0x71, v160
	v_mul_f32_e32 v136, v119, v135
	v_cmp_gt_i32_e32 vcc, v137, v122
	v_mul_f32_e32 v136, v136, v157
	s_and_b64 s[42:43], s[16:17], vcc
	v_add_u32_e32 v137, 0x72, v160
	v_cndmask_b32_e64 v157, v136, 0, s[42:43]
	v_mul_f32_e32 v136, v120, v135
	v_cmp_gt_i32_e32 vcc, v137, v122
	v_mul_f32_e32 v136, v136, v158
	s_and_b64 s[42:43], s[16:17], vcc
	v_cndmask_b32_e64 v158, v136, 0, s[42:43]
	v_add_u32_e32 v136, 0x73, v160
	v_mul_f32_e32 v135, v121, v135
	v_cmp_gt_i32_e32 vcc, v136, v122
	v_mul_f32_e32 v135, v135, v159
	s_and_b64 s[16:17], s[16:17], vcc
	v_cndmask_b32_e64 v135, v135, 0, s[16:17]
	v_cvt_pk_bf16_f32 v136, v66, v67
	v_cvt_pk_bf16_f32 v137, v68, v69
	v_cvt_pk_bf16_f32 v138, v70, v71
	v_cvt_pk_bf16_f32 v139, v72, v73
	v_cvt_pk_bf16_f32 v140, v161, v162
	v_cvt_pk_bf16_f32 v141, v163, v164
	v_cvt_pk_bf16_f32 v142, v165, v166
	v_cvt_pk_bf16_f32 v143, v167, v143
	v_cvt_pk_bf16_f32 v70, v144, v145
	v_cvt_pk_bf16_f32 v71, v146, v147
	v_cvt_pk_bf16_f32 v72, v148, v149
	v_cvt_pk_bf16_f32 v73, v150, v151
	v_cvt_pk_bf16_f32 v66, v152, v153
	v_cvt_pk_bf16_f32 v67, v154, v155
	v_cvt_pk_bf16_f32 v68, v156, v157
	v_cvt_pk_bf16_f32 v69, v158, v135
	v_add3_u32 v135, s40, v87, v127
	v_add_u32_e32 v176, 0x4800, v135
	v_add_u32_e32 v177, 0x5800, v135
	v_add_u32_e32 v178, 0x6800, v135
	v_add_u32_e32 v179, 0x7800, v135
	v_add_u32_e32 v180, 0x8800, v135
	v_add_u32_e32 v181, 0x9800, v135
	v_add_u32_e32 v182, 0xa800, v135
	v_add_u32_e32 v135, 0xb800, v135
	ds_read_b64 v[144:145], v176
	ds_read_b64 v[146:147], v176 offset:32
	ds_read_b64 v[148:149], v177 offset:256
	ds_read_b64 v[150:151], v177 offset:288
	ds_read_b64 v[152:153], v178 offset:512
	ds_read_b64 v[154:155], v178 offset:544
	ds_read_b64 v[156:157], v179 offset:768
	ds_read_b64 v[158:159], v179 offset:800
	ds_read_b64 v[160:161], v180 offset:1024
	ds_read_b64 v[162:163], v180 offset:1056
	ds_read_b64 v[164:165], v181 offset:1280
	ds_read_b64 v[166:167], v181 offset:1312
	ds_read_b64 v[168:169], v182 offset:1536
	ds_read_b64 v[170:171], v182 offset:1568
	ds_read_b64 v[172:173], v135 offset:1792
	ds_read_b64 v[174:175], v135 offset:1824
	s_setprio 1
	s_waitcnt lgkmcnt(0)
; template <int D, int DV, int MODE, int NMAP, int KT> ...
;     ...
;                 constexpr int CBB = 4, NCB = (DV / 16) / CBB, NVB = KK2 * NCB;
;                 bf16x8 vfr[2][CBB];
;     ...
;                 AT_VLOAD(0, 0);
; #pragma unroll
;                 for (int b_ = 0; b_ < NVB; ++b_) {
;                     if (b_ + 1 < NVB) AT_VLOAD(b_ + 1, (b_ + 1) & 1);
;                     __builtin_amdgcn_sched_barrier(0);
;                     const int kk_ = b_ / NCB, c0_ = (b_ % NCB) * CBB;
;                     __builtin_amdgcn_s_setprio(1);
; #pragma unroll
;                     for (int x_ = 0; x_ < CBB; ++x_)
; #pragma unroll
;                         for (int mp = 0; mp < NMAP; ++mp) o[mp][c0_ + x_] = __builtin_amdgcn_mfma_f32_16x16x32_bf16(vfr[b_ & 1][x_], pb[mp][kk_], o[mp][c0_ + x_], 0, 0, 0);
;                     __builtin_amdgcn_s_setprio(0);
;                     __builtin_amdgcn_sched_barrier(0);
;                 }
	v_mfma_f32_16x16x32_bf16 v[30:33], v[144:147], v[136:139], v[30:33]
	v_mfma_f32_16x16x32_bf16 v[26:29], v[148:151], v[136:139], v[26:29]
	v_mfma_f32_16x16x32_bf16 v[22:25], v[152:155], v[136:139], v[22:25]
	v_mfma_f32_16x16x32_bf16 v[18:21], v[156:159], v[136:139], v[18:21]
	s_setprio 0
	ds_read_b64 v[144:145], v176 offset:64
	ds_read_b64 v[146:147], v176 offset:96
	ds_read_b64 v[148:149], v177 offset:320
	ds_read_b64 v[150:151], v177 offset:352
	ds_read_b64 v[152:153], v178 offset:576
	ds_read_b64 v[154:155], v178 offset:608
	ds_read_b64 v[156:157], v179 offset:832
	ds_read_b64 v[158:159], v179 offset:864
	s_setprio 1
	v_mfma_f32_16x16x32_bf16 v[14:17], v[160:163], v[136:139], v[14:17]
	v_mfma_f32_16x16x32_bf16 v[10:13], v[164:167], v[136:139], v[10:13]
	v_mfma_f32_16x16x32_bf16 v[6:9], v[168:171], v[136:139], v[6:9]
	v_mfma_f32_16x16x32_bf16 v[2:5], v[172:175], v[136:139], v[2:5]
	s_setprio 0
	ds_read_b64 v[136:137], v180 offset:1088
	ds_read_b64 v[138:139], v180 offset:1120
	ds_read_b64 v[160:161], v181 offset:1344
	ds_read_b64 v[162:163], v181 offset:1376
	ds_read_b64 v[164:165], v182 offset:1600
	ds_read_b64 v[166:167], v182 offset:1632
	ds_read_b64 v[168:169], v135 offset:1856
	ds_read_b64 v[170:171], v135 offset:1888
	s_setprio 1
	s_waitcnt lgkmcnt(0)
	v_mfma_f32_16x16x32_bf16 v[30:33], v[144:147], v[140:143], v[30:33]
	v_mfma_f32_16x16x32_bf16 v[26:29], v[148:151], v[140:143], v[26:29]
	v_mfma_f32_16x16x32_bf16 v[22:25], v[152:155], v[140:143], v[22:25]
	v_mfma_f32_16x16x32_bf16 v[18:21], v[156:159], v[140:143], v[18:21]
	s_setprio 0
	ds_read_b64 v[144:145], v176 offset:128
	ds_read_b64 v[146:147], v176 offset:160
	ds_read_b64 v[148:149], v177 offset:384
	ds_read_b64 v[150:151], v177 offset:416
	ds_read_b64 v[152:153], v178 offset:640
	ds_read_b64 v[154:155], v178 offset:672
	ds_read_b64 v[156:157], v179 offset:896
	ds_read_b64 v[158:159], v179 offset:928
	s_setprio 1
	v_mfma_f32_16x16x32_bf16 v[14:17], v[136:139], v[140:143], v[14:17]
	v_mfma_f32_16x16x32_bf16 v[10:13], v[160:163], v[140:143], v[10:13]
	v_mfma_f32_16x16x32_bf16 v[6:9], v[164:167], v[140:143], v[6:9]
	v_mfma_f32_16x16x32_bf16 v[2:5], v[168:171], v[140:143], v[2:5]
	s_setprio 0
	ds_read_b64 v[136:137], v180 offset:1152
	ds_read_b64 v[138:139], v180 offset:1184
	ds_read_b64 v[140:141], v181 offset:1408
	ds_read_b64 v[142:143], v181 offset:1440
	ds_read_b64 v[160:161], v182 offset:1664
	ds_read_b64 v[162:163], v182 offset:1696
	ds_read_b64 v[164:165], v135 offset:1920
	ds_read_b64 v[166:167], v135 offset:1952
	s_setprio 1
	s_waitcnt lgkmcnt(0)
	v_mfma_f32_16x16x32_bf16 v[30:33], v[144:147], v[70:73], v[30:33]
	v_mfma_f32_16x16x32_bf16 v[26:29], v[148:151], v[70:73], v[26:29]
	v_mfma_f32_16x16x32_bf16 v[22:25], v[152:155], v[70:73], v[22:25]
	v_mfma_f32_16x16x32_bf16 v[18:21], v[156:159], v[70:73], v[18:21]
	s_setprio 0
	ds_read_b64 v[144:145], v176 offset:192
	ds_read_b64 v[146:147], v176 offset:224
	ds_read_b64 v[148:149], v177 offset:448
	ds_read_b64 v[150:151], v177 offset:480
	ds_read_b64 v[152:153], v178 offset:704
	ds_read_b64 v[154:155], v178 offset:736
	ds_read_b64 v[156:157], v179 offset:960
	ds_read_b64 v[158:159], v179 offset:992
	s_setprio 1
	v_mfma_f32_16x16x32_bf16 v[14:17], v[136:139], v[70:73], v[14:17]
	v_mfma_f32_16x16x32_bf16 v[10:13], v[140:143], v[70:73], v[10:13]
	v_mfma_f32_16x16x32_bf16 v[6:9], v[160:163], v[70:73], v[6:9]
	v_mfma_f32_16x16x32_bf16 v[2:5], v[164:167], v[70:73], v[2:5]
	s_setprio 0
	ds_read_b64 v[70:71], v180 offset:1216
	ds_read_b64 v[72:73], v180 offset:1248
	ds_read_b64 v[136:137], v181 offset:1472
	ds_read_b64 v[138:139], v181 offset:1504
	ds_read_b64 v[140:141], v182 offset:1728
	ds_read_b64 v[142:143], v182 offset:1760
	ds_read_b64 v[160:161], v135 offset:1984
	ds_read_b64 v[162:163], v135 offset:2016
	s_setprio 1
	s_waitcnt lgkmcnt(0)
	v_mfma_f32_16x16x32_bf16 v[30:33], v[144:147], v[66:69], v[30:33]
	v_mfma_f32_16x16x32_bf16 v[26:29], v[148:151], v[66:69], v[26:29]
	v_mfma_f32_16x16x32_bf16 v[22:25], v[152:155], v[66:69], v[22:25]
	v_mfma_f32_16x16x32_bf16 v[18:21], v[156:159], v[66:69], v[18:21]
	s_setprio 0
	s_setprio 1
	v_mfma_f32_16x16x32_bf16 v[14:17], v[70:73], v[66:69], v[14:17]
	v_mfma_f32_16x16x32_bf16 v[10:13], v[136:139], v[66:69], v[10:13]
	v_mfma_f32_16x16x32_bf16 v[6:9], v[140:143], v[66:69], v[6:9]
	v_mfma_f32_16x16x32_bf16 v[2:5], v[160:163], v[66:69], v[2:5]
	s_setprio 0

; template <int D, int DV, int MODE, int NMAP, int KT> ...
;     ...
;     AT_LOAD(0);
;     __syncthreads();
;     AT_STORE(0);
;     if (nkt > 1) AT_LOAD(1);
; __global__ void __launch_bounds__(512, 2) mega_fwd(Params P) {
;     ...
;                         for (int u = blk; u < 2048; u += G) {
;                             const int bh = u & 127, b = bh >> 2, h = bh & 3, qi_ = u >> 7, ii_ = qi_ >> 1, hb_ = qi_ & 1, qt = (ii_ & 1) ? (ii_ - 1 + hb_) : (15 - hb_ - ii_), q0 = qt * 128, nkt = (q0 + 128) / 64;
;                             const size_t rb = (size_t)b * SEQ;
;                             f32x4 o[2][8]; float ll[2];
;                             attn_core3<64, 128, 1, 2, 64>(lds, Z + (rb + q0) * ZW + h * 128, ZW, Z + rb * ZW + 512 + h * 128, ZW, Z + rb * ZW + 1024 + h * 128, ZW, q0, nkt, 0.125f * LOG2E, 0.f, o, ll);
.LBB0_1089:
	s_ashr_i32 s2, s1, 8
	s_bfe_u32 s3, s1, 0x10007
	s_add_i32 s5, s2, s3
	s_xor_b32 s3, s3, 15
	s_and_b32 s4, s1, 0x100
	s_add_i32 s5, s5, -1
	s_sub_i32 s2, s3, s2
	s_cmp_eq_u32 s4, 0
	s_cselect_b32 s2, s2, s5
	s_lshl_b32 s8, s2, 7
	s_add_i32 s2, s8, 0x80
	s_ashr_i32 s44, s2, 6
	s_lshl_b32 s2, s1, 9
	s_and_b32 s2, s2, 0xf800
	s_ashr_i32 s3, s8, 31
	s_add_u32 s46, s8, s2
	s_addc_u32 s47, s3, 0
	s_mul_i32 s3, s47, 0x1400
	s_mul_hi_u32 s4, s46, 0x1400
	s_add_i32 s4, s4, s3
	s_mul_i32 s3, s46, 0x1400
	s_add_u32 s3, s34, s3
	s_addc_u32 s5, s40, s4
	s_lshl_b32 s4, s1, 7
	s_and_b32 s4, s4, 0x180
	s_lshl_b32 s43, s4, 1
	s_add_u32 s4, s3, s43
	s_addc_u32 s5, s5, 0
	s_mulk_i32 s2, 0x1400
	s_add_u32 s2, s34, s2
	s_addc_u32 s3, s40, 0
	v_mov_b32_e32 v28, v211
	s_add_u32 s2, s2, s43
	s_addc_u32 s3, s3, 0
	v_readfirstlane_b32 s6, v28
	s_ashr_i32 s6, s6, 6
	v_and_b32_e32 v27, 15, v28
	s_lshl_b32 s74, s6, 4
	v_or_b32_e32 v0, s74, v27
	v_mov_b64_e32 v[2:3], s[4:5]
	v_mad_i64_i32 v[2:3], s[4:5], v0, s57, v[2:3]
	v_and_b32_e32 v0, 48, v28
	v_add_u32_e32 v24, 0x200, v28
	v_lshl_add_u64 v[14:15], v[2:3], 0, v[0:1]
	v_ashrrev_i32_e32 v0, 31, v28
	v_ashrrev_i32_e32 v25, 31, v24
	v_lshrrev_b32_e32 v0, 28, v0
	v_lshrrev_b32_e32 v25, 28, v25
	v_add_u32_e32 v18, v28, v0
	v_add_u32_e32 v25, v24, v25
	v_ashrrev_i32_e32 v0, 4, v18
	v_and_b32_e32 v18, -16, v18
	v_mov_b64_e32 v[34:35], s[2:3]
	v_ashrrev_i32_e32 v29, 4, v25
	v_sub_u32_e32 v38, v28, v18
	v_mad_i64_i32 v[18:19], s[4:5], v0, s57, v[34:35]
	v_mad_i64_i32 v[30:31], s[4:5], v29, s57, v[34:35]
	s_ashr_i32 s4, s6, 31
	s_lshr_b32 s4, s4, 28
	s_add_i32 s4, s6, s4
	s_ashr_i32 s11, s4, 4
	s_and_b32 s4, s4, -16
	v_and_b32_e32 v26, 63, v28
	s_sub_i32 s45, s6, s4
	s_lshl_b32 s9, s11, 6
	s_add_i32 s6, s6, 8
	v_or_b32_e32 v36, s9, v26
	s_ashr_i32 s7, s6, 31
	v_mad_i64_i32 v[36:37], s[4:5], v36, s57, v[34:35]
	s_lshr_b32 s7, s7, 28
	s_lshl_b32 s4, s45, 3
	s_add_i32 s7, s6, s7
	v_and_b32_e32 v25, -16, v25
	s_ashr_i32 s5, s4, 31
	s_ashr_i32 s12, s7, 4
	v_lshlrev_b32_e32 v22, 3, v38
	v_sub_u32_e32 v39, v24, v25
	v_lshl_add_u64 v[36:37], s[4:5], 1, v[36:37]
	s_lshl_b32 s10, s12, 6
	global_load_dwordx4 v[2:5], v[14:15], off
	global_load_dwordx4 v[6:9], v[14:15], off offset:64
	global_load_dwordx4 v[10:13], v[14:15], off offset:128
	s_nop 0
	global_load_dwordx4 v[14:17], v[14:15], off offset:192
	v_ashrrev_i32_e32 v23, 31, v22
	v_lshlrev_b32_e32 v24, 3, v39
	global_load_dwordx4 v[58:61], v[36:37], off offset:2048
	s_and_b32 s7, s7, -16
	v_or_b32_e32 v36, s10, v26
	v_lshl_add_u64 v[18:19], v[22:23], 1, v[18:19]
	v_ashrrev_i32_e32 v25, 31, v24
	s_sub_i32 s61, s6, s7
	v_mad_i64_i32 v[34:35], s[6:7], v36, s57, v[34:35]
	global_load_dwordx4 v[18:21], v[18:19], off offset:1024
	v_lshl_add_u64 v[30:31], v[24:25], 1, v[30:31]
	s_lshl_b32 s6, s61, 3
	global_load_dwordx4 v[30:33], v[30:31], off offset:1024
	s_ashr_i32 s7, s6, 31
	v_lshl_add_u64 v[34:35], s[6:7], 1, v[34:35]
	global_load_dwordx4 v[62:65], v[34:35], off offset:2048
	s_movk_i32 s13, 0x110
	v_mul_lo_u32 v135, v0, s13
	v_lshlrev_b32_e32 v144, 4, v38
	v_lshrrev_b32_e32 v34, 2, v0
	v_lshrrev_b32_e32 v147, 3, v0
	v_xor_b32_e32 v147, v34, v147
	v_and_b32_e32 v147, 1, v147
	v_lshlrev_b32_e32 v147, 4, v147
	v_xor_b32_e32 v144, v144, v147
	s_mulk_i32 s45, 0x480
	v_add3_u32 v34, 0, v135, v144
	v_mul_lo_u32 v145, v29, s13
	v_lshlrev_b32_e32 v146, 4, v39
	v_xor_b32_e32 v146, v146, v147
	s_add_i32 s13, s45, 0
	s_lshl_b32 s56, s11, 7
	s_mulk_i32 s61, 0x480
	s_waitcnt lgkmcnt(0)
	s_barrier
	s_add_i32 s13, s13, s56
	v_lshlrev_b32_e32 v147, 1, v26
	s_add_i32 s11, s61, 0
	s_lshl_b32 s67, s12, 7
	s_add_i32 s11, s11, s67
	s_cmp_lt_i32 s44, 2
	s_waitcnt vmcnt(0)
	ds_write_b128 v34, v[18:21]
	v_add3_u32 v34, 0, v145, v146
	ds_write_b128 v34, v[30:33]
	v_add_u32_e32 v34, s13, v147
	ds_write_b16 v34, v58 offset:17408
	ds_write_b16_d16_hi v34, v58 offset:17552
	ds_write_b16 v34, v59 offset:17696
	ds_write_b16_d16_hi v34, v59 offset:17840
	ds_write_b16 v34, v60 offset:17984
	ds_write_b16_d16_hi v34, v60 offset:18128
	ds_write_b16 v34, v61 offset:18272
	ds_write_b16_d16_hi v34, v61 offset:18416
	v_add_u32_e32 v34, s11, v147
	ds_write_b16 v34, v62 offset:17408
	ds_write_b16_d16_hi v34, v62 offset:17552
	ds_write_b16 v34, v63 offset:17696
	ds_write_b16_d16_hi v34, v63 offset:17840
	ds_write_b16 v34, v64 offset:17984
	ds_write_b16_d16_hi v34, v64 offset:18128
	ds_write_b16 v34, v65 offset:18272
	ds_write_b16_d16_hi v34, v65 offset:18416
	s_cbranch_scc1 .LBB0_1091
	v_or_b32_e32 v38, 64, v26
	v_add_u32_e32 v18, 64, v0
	v_mov_b64_e32 v[34:35], s[2:3]
	v_add_u32_e32 v20, 64, v29
	v_add_u32_e32 v36, s9, v38
	v_mad_i64_i32 v[18:19], s[12:13], v18, s57, v[34:35]
	v_mad_i64_i32 v[20:21], s[12:13], v20, s57, v[34:35]
	v_mad_i64_i32 v[36:37], s[12:13], v36, s57, v[34:35]
	v_add_u32_e32 v38, s10, v38
	v_lshl_add_u64 v[18:19], v[22:23], 1, v[18:19]
	v_lshl_add_u64 v[30:31], v[24:25], 1, v[20:21]
	v_lshl_add_u64 v[36:37], s[4:5], 1, v[36:37]
	v_mad_i64_i32 v[34:35], s[12:13], v38, s57, v[34:35]
	global_load_dwordx4 v[18:21], v[18:19], off offset:1024
	s_nop 0
	global_load_dwordx4 v[30:33], v[30:31], off offset:1024
	v_lshl_add_u64 v[34:35], s[6:7], 1, v[34:35]
	global_load_dwordx4 v[58:61], v[36:37], off offset:2048
	global_load_dwordx4 v[62:65], v[34:35], off offset:2048
; #define LAS __attribute__((address_space(3)))
; template <int D, int DV, int MODE, int NMAP, int KT> ...
;     ...
;     float m[NMAP];
; #pragma unroll
;     for (int mp = 0; mp < NMAP; ++mp) { m[mp] = -INFINITY; l[mp] = 0.f;
; #pragma unroll
;         for (int cb = 0; cb < DV / 16; ++cb) o[mp][cb] = (f32x4){0.f, 0.f, 0.f, 0.f}; }
;     const int rowmin = q0 + w * 16, myrow = rowmin + r;
;     ...
;         if (MODE == 0 || kt * KT <= rowmin + 15) {
;             const LAS bf16_t* Ks = (const LAS bf16_t*)(lds + cur); const LAS bf16_t* Vt = (const LAS bf16_t*)(lds + cur + KS_BYTES);
;             const bool diag = (MODE != 0) && (kt * KT + KT - 1 > rowmin);
;             bf16x8 pb[NMAP][KK2];
;             f32x4 sall[NMAP][NB];
; #pragma unroll
;             for (int mp = 0; mp < NMAP; ++mp) {
;                 f32x4 (&s)[NB] = sall[mp];
;                 constexpr int KD = D / 32, NBB = (KD >= 8) ? 1 : (8 / KD), NSB = NB / NBB;
;                 bf16x8 kfr[2][NBB][KD];
.LBB0_1091:
	s_cmp_lt_i32 s44, 1
	s_cbranch_scc1 .LBB0_1108
	s_add_i32 s74, s74, s8
	s_or_b32 s75, s74, 15
	s_lshl_b64 s[4:5], s[4:5], 1
	s_add_u32 s48, s2, s4
	s_addc_u32 s49, s3, s5
	s_lshl_b64 s[4:5], s[6:7], 1
	s_add_u32 s50, s2, s4
	v_bfe_u32 v28, v28, 4, 2
	s_addc_u32 s51, s3, s5
	s_addk_i32 s9, 0x80
	s_addk_i32 s10, 0x80
	v_mov_b32_e32 v90, v1
	v_mov_b32_e32 v91, v1
	v_mov_b32_e32 v92, v1
	v_mov_b32_e32 v93, v1
	v_lshlrev_b32_e32 v148, 3, v28
	v_or_b32_e32 v149, s74, v27
	v_lshlrev_b32_e32 v150, 2, v28
	v_lshl_add_u64 v[138:139], v[22:23], 1, s[2:3]
	v_lshl_add_u64 v[140:141], v[24:25], 1, s[2:3]
	v_mul_u32_u24_e32 v151, 0x110, v27
	v_lshrrev_b32_e32 v152, 2, v27
	v_lshrrev_b32_e32 v153, 3, v27
	v_xor_b32_e32 v152, v152, v153
	v_and_b32_e32 v152, 1, v152
	v_xor_b32_e32 v153, v152, v28
	v_sub_u32_e32 v153, v153, v28
	v_lshlrev_b32_e32 v153, 4, v153
	v_add_u32_e32 v151, v151, v153
	v_mul_u32_u24_e32 v152, 0x90, v27
	v_add_u32_e32 v153, 0x80, v29
	v_add_u32_e32 v154, 0x80, v0
	v_add_u32_e32 v155, s9, v26
	v_add_u32_e32 v156, s10, v26
	v_mov_b32_e32 v0, v1
	v_mov_b64_e32 v[82:83], v[90:91]
	v_mov_b64_e32 v[74:75], v[90:91]
	v_mov_b64_e32 v[66:67], v[90:91]
	v_mov_b64_e32 v[50:51], v[90:91]
	v_mov_b64_e32 v[42:43], v[90:91]
	v_mov_b64_e32 v[34:35], v[90:91]
	v_mov_b64_e32 v[22:23], v[90:91]
	v_mov_b64_e32 v[96:97], v[92:93]
	v_mov_b64_e32 v[86:87], v[90:91]
	v_mov_b64_e32 v[78:79], v[90:91]
	v_mov_b64_e32 v[70:71], v[90:91]
	v_mov_b64_e32 v[54:55], v[90:91]
	v_mov_b64_e32 v[46:47], v[90:91]
	v_mov_b64_e32 v[38:39], v[90:91]
	v_mov_b64_e32 v[26:27], v[90:91]
	v_mov_b32_e32 v157, 0xff800000
	s_mov_b32 s76, 0
	v_mov_b64_e32 v[84:85], v[92:93]
	v_mov_b64_e32 v[76:77], v[92:93]
	v_mov_b64_e32 v[68:69], v[92:93]
	v_mov_b64_e32 v[52:53], v[92:93]
	v_mov_b64_e32 v[44:45], v[92:93]
	v_mov_b64_e32 v[36:37], v[92:93]
	v_mov_b64_e32 v[24:25], v[92:93]
	v_mov_b64_e32 v[94:95], v[90:91]
	v_mov_b64_e32 v[88:89], v[92:93]
	v_mov_b64_e32 v[80:81], v[92:93]
	v_mov_b64_e32 v[72:73], v[92:93]
	v_mov_b64_e32 v[56:57], v[92:93]
	v_mov_b64_e32 v[48:49], v[92:93]
	v_mov_b64_e32 v[40:41], v[92:93]
	v_mov_b64_e32 v[28:29], v[92:93]
	v_mov_b64_e32 v[136:137], v[0:1]
	v_mov_b32_e32 v0, 0xff800000
	s_mov_b32 s2, 0

; __device__ __forceinline__ unsigned cvt_pk_bf16(float lo, float hi) { unsigned r; asm volatile("v_cvt_pk_bf16_f32 %0, %1, %2" : "=v"(r) : "v"(lo), "v"(hi)); return r; }
; template <int D, int DV, int MODE, int NMAP, int KT> ...
;     ...
;                     const float nm = -m[mp]; float ps = 0.f;
; #pragma unroll
;                     for (int nb = 0; nb < NB; ++nb)
; #pragma unroll
;                         for (int j = 0; j < 4; ++j) { const float p = __builtin_amdgcn_exp2f(fmaf(s[nb][j], sc, nm)); ps += p; s[nb][j] = p; }
;                     l[mp] += ps;
;                 } else {
;                     const float rowf = __builtin_amdgcn_exp2f(l2g * (float)(myrow - kt * KT));
; #pragma unroll
;                     for (int nb = 0; nb < NB; ++nb)
; #pragma unroll
;                         for (int j = 0; j < 4; ++j) { float p = s[nb][j] * (rowf * ck[nb][j]); if (diag && (kt * KT + nb * 16 + g4 * 4 + j > myrow)) p = 0.f; s[nb][j] = p; }
;                 }
; #pragma unroll
;                 for (int kk = 0; kk < KK2; ++kk) { u32x4 wv; wv.x = cvt_pk_bf16(s[2 * kk][0], s[2 * kk][1]); wv.y = cvt_pk_bf16(s[2 * kk][2], s[2 * kk][3]);
;                     wv.z = cvt_pk_bf16(s[2 * kk + 1][0], s[2 * kk + 1][1]); wv.w = cvt_pk_bf16(s[2 * kk + 1][2], s[2 * kk + 1][3]); pb[mp][kk] = __builtin_bit_cast(bf16x8, wv); }
;             }
;             {
;                 constexpr int CBB = 4, NCB = (DV / 16) / CBB, NVB = KK2 * NCB;
;                 bf16x8 vfr[2][CBB];
;     ...
;                 AT_VLOAD(0, 0);
; #pragma unroll
;                 for (int b_ = 0; b_ < NVB; ++b_) {
;                     if (b_ + 1 < NVB) AT_VLOAD(b_ + 1, (b_ + 1) & 1);
;                     __builtin_amdgcn_sched_barrier(0);
;                     const int kk_ = b_ / NCB, c0_ = (b_ % NCB) * CBB;
;                     __builtin_amdgcn_s_setprio(1);
; #pragma unroll
;                     for (int x_ = 0; x_ < CBB; ++x_)
; #pragma unroll
;                         for (int mp = 0; mp < NMAP; ++mp) o[mp][c0_ + x_] = __builtin_amdgcn_mfma_f32_16x16x32_bf16(vfr[b_ & 1][x_], pb[mp][kk_], o[mp][c0_ + x_], 0, 0, 0);
;                     __builtin_amdgcn_s_setprio(0);
;                     __builtin_amdgcn_sched_barrier(0);
;                 }
.LBB0_1105:
	v_fma_f32 v114, v114, s71, -v0
	v_exp_f32_e32 v114, v114
	v_fma_f32 v115, v115, s71, -v0
	v_exp_f32_e32 v115, v115
	v_fma_f32 v116, v116, s71, -v0
	v_exp_f32_e32 v116, v116
	v_fma_f32 v117, v117, s71, -v0
	v_exp_f32_e32 v117, v117
	v_fma_f32 v110, v110, s71, -v0
	v_add_f32_e32 v122, 0, v114
	v_exp_f32_e32 v110, v110
	v_fma_f32 v111, v111, s71, -v0
	v_add_f32_e32 v122, v115, v122
	v_exp_f32_e32 v111, v111
	v_fma_f32 v112, v112, s71, -v0
	v_add_f32_e32 v122, v116, v122
	v_exp_f32_e32 v112, v112
	v_fma_f32 v113, v113, s71, -v0
	v_add_f32_e32 v122, v117, v122
	v_exp_f32_e32 v113, v113
	v_fma_f32 v102, v102, s71, -v0
	v_add_f32_e32 v122, v110, v122
	v_exp_f32_e32 v102, v102
	v_fma_f32 v103, v103, s71, -v0
	v_add_f32_e32 v122, v111, v122
	v_exp_f32_e32 v103, v103
	v_fma_f32 v104, v104, s71, -v0
	v_add_f32_e32 v122, v112, v122
	v_exp_f32_e32 v104, v104
	v_fma_f32 v105, v105, s71, -v0
	v_add_f32_e32 v122, v113, v122
	v_exp_f32_e32 v105, v105
	v_fma_f32 v98, v98, s71, -v0
	v_add_f32_e32 v122, v102, v122
	v_exp_f32_e32 v123, v98
	v_add_f32_e32 v122, v103, v122
	v_add_f32_e32 v122, v104, v122
	v_add_f32_e32 v122, v105, v122
	v_fma_f32 v99, v99, s71, -v0
	v_add_f32_e32 v98, v123, v122
	v_exp_f32_e32 v122, v99
	v_fma_f32 v99, v100, s71, -v0
	v_exp_f32_e32 v124, v99
	v_fma_f32 v99, v101, s71, -v0
	v_exp_f32_e32 v125, v99
	v_add_f32_e32 v98, v122, v98
	v_add_f32_e32 v98, v124, v98
	v_add3_u32 v170, s83, v148, v152
	v_add_f32_e32 v98, v125, v98
	v_add_u32_e32 v174, 0x4000, v170
	v_add_u32_e32 v175, 0x4800, v170
	v_add_u32_e32 v176, 0x5000, v170
	v_add_u32_e32 v177, 0x5800, v170
	v_add_u32_e32 v178, 0x6800, v170
	v_add_u32_e32 v179, 0x7000, v170
	v_add_u32_e32 v180, 0x7800, v170
	v_add_u32_e32 v181, 0x8000, v170
	v_add_f32_e32 v137, v137, v98
	v_cvt_pk_bf16_f32 v98, v114, v115
	v_cvt_pk_bf16_f32 v99, v116, v117
	v_cvt_pk_bf16_f32 v100, v110, v111
	v_cvt_pk_bf16_f32 v101, v112, v113
	v_cvt_pk_bf16_f32 v102, v102, v103
	v_cvt_pk_bf16_f32 v103, v104, v105
	v_cvt_pk_bf16_f32 v104, v123, v122
	v_cvt_pk_bf16_f32 v105, v124, v125
	ds_read_b64 v[110:111], v174 offset:1024
	ds_read_b64 v[112:113], v174 offset:1056
	ds_read_b64 v[114:115], v175 offset:1280
	ds_read_b64 v[116:117], v175 offset:1312
	ds_read_b64 v[122:123], v176 offset:1536
	ds_read_b64 v[124:125], v176 offset:1568
	ds_read_b64 v[126:127], v177 offset:1792
	ds_read_b64 v[128:129], v177 offset:1824
	ds_read_b64 v[158:159], v178
	ds_read_b64 v[160:161], v178 offset:32
	ds_read_b64 v[162:163], v179 offset:256
	ds_read_b64 v[164:165], v179 offset:288
	ds_read_b64 v[166:167], v180 offset:512
	ds_read_b64 v[168:169], v180 offset:544
	ds_read_b64 v[170:171], v181 offset:768
	ds_read_b64 v[172:173], v181 offset:800
	s_setprio 1
	s_waitcnt lgkmcnt(0)
	v_mfma_f32_16x16x32_bf16 v[90:93], v[110:113], v[118:121], v[90:93]
	v_mfma_f32_16x16x32_bf16 v[94:97], v[110:113], v[98:101], v[94:97]
	v_mfma_f32_16x16x32_bf16 v[82:85], v[114:117], v[118:121], v[82:85]
	v_mfma_f32_16x16x32_bf16 v[86:89], v[114:117], v[98:101], v[86:89]
	v_mfma_f32_16x16x32_bf16 v[74:77], v[122:125], v[118:121], v[74:77]
	v_mfma_f32_16x16x32_bf16 v[78:81], v[122:125], v[98:101], v[78:81]
	v_mfma_f32_16x16x32_bf16 v[66:69], v[126:129], v[118:121], v[66:69]
	v_mfma_f32_16x16x32_bf16 v[70:73], v[126:129], v[98:101], v[70:73]
	s_setprio 0
	ds_read_b64 v[110:111], v174 offset:1088
	ds_read_b64 v[112:113], v174 offset:1120
	ds_read_b64 v[114:115], v175 offset:1344
	ds_read_b64 v[116:117], v175 offset:1376
	ds_read_b64 v[122:123], v176 offset:1600
	ds_read_b64 v[124:125], v176 offset:1632
	ds_read_b64 v[126:127], v177 offset:1856
	ds_read_b64 v[128:129], v177 offset:1888
	s_setprio 1
	v_mfma_f32_16x16x32_bf16 v[50:53], v[158:161], v[118:121], v[50:53]
	v_mfma_f32_16x16x32_bf16 v[54:57], v[158:161], v[98:101], v[54:57]
	v_mfma_f32_16x16x32_bf16 v[42:45], v[162:165], v[118:121], v[42:45]
	v_mfma_f32_16x16x32_bf16 v[46:49], v[162:165], v[98:101], v[46:49]
	v_mfma_f32_16x16x32_bf16 v[34:37], v[166:169], v[118:121], v[34:37]
	v_mfma_f32_16x16x32_bf16 v[38:41], v[166:169], v[98:101], v[38:41]
	v_mfma_f32_16x16x32_bf16 v[22:25], v[170:173], v[118:121], v[22:25]
	v_mfma_f32_16x16x32_bf16 v[26:29], v[170:173], v[98:101], v[26:29]
	s_setprio 0
	ds_read_b64 v[98:99], v178 offset:64
	ds_read_b64 v[100:101], v178 offset:96
	ds_read_b64 v[118:119], v179 offset:320
	ds_read_b64 v[120:121], v179 offset:352
	ds_read_b64 v[158:159], v180 offset:576
	ds_read_b64 v[160:161], v180 offset:608
	ds_read_b64 v[162:163], v181 offset:832
	ds_read_b64 v[164:165], v181 offset:864
	s_setprio 1
	s_waitcnt lgkmcnt(0)
	v_mfma_f32_16x16x32_bf16 v[90:93], v[110:113], v[106:109], v[90:93]
	v_mfma_f32_16x16x32_bf16 v[94:97], v[110:113], v[102:105], v[94:97]
	v_mfma_f32_16x16x32_bf16 v[82:85], v[114:117], v[106:109], v[82:85]
	v_mfma_f32_16x16x32_bf16 v[86:89], v[114:117], v[102:105], v[86:89]
	v_mfma_f32_16x16x32_bf16 v[74:77], v[122:125], v[106:109], v[74:77]
	v_mfma_f32_16x16x32_bf16 v[78:81], v[122:125], v[102:105], v[78:81]
	v_mfma_f32_16x16x32_bf16 v[66:69], v[126:129], v[106:109], v[66:69]
	v_mfma_f32_16x16x32_bf16 v[70:73], v[126:129], v[102:105], v[70:73]
	s_setprio 0
	s_setprio 1
	v_mfma_f32_16x16x32_bf16 v[50:53], v[98:101], v[106:109], v[50:53]
	v_mfma_f32_16x16x32_bf16 v[54:57], v[98:101], v[102:105], v[54:57]
	v_mfma_f32_16x16x32_bf16 v[42:45], v[118:121], v[106:109], v[42:45]
	v_mfma_f32_16x16x32_bf16 v[46:49], v[118:121], v[102:105], v[46:49]
	v_mfma_f32_16x16x32_bf16 v[34:37], v[158:161], v[106:109], v[34:37]
	v_mfma_f32_16x16x32_bf16 v[38:41], v[158:161], v[102:105], v[38:41]
	v_mfma_f32_16x16x32_bf16 v[22:25], v[162:165], v[106:109], v[22:25]
	v_mfma_f32_16x16x32_bf16 v[26:29], v[162:165], v[102:105], v[26:29]
	s_setprio 0
